# batch the 8 row loads in x->bf16 loop (was load/wait/store serialized); hoist final-rmsnorm gain loads out of loop
# speedup vs baseline: 1.0038x; 1.0038x over previous
; __device__ __forceinline__ int tid_fresh() { int t = threadIdx.x; asm volatile("" : "+v"(t)); return t; }
; __device__ __forceinline__ int bid_fresh() { int t = blockIdx.x; asm volatile("" : "+s"(t)); return t; }
; __device__ __forceinline__ unsigned pk2(float lo, float hi) { const hf32x2 v = {lo, hi}; return __builtin_bit_cast(unsigned, __builtin_convertvector(v, hbf16x2)); }
; __device__ __forceinline__ void phase0(PP p, unsigned char* shm) {
;     ...
;         const int lane = tid_fresh() & 63, gw = bid_fresh() * 8 + (tid_fresh() >> 6), NGW = gridDim.x * 8;
;         float* ssb = (float*)(ws + WS_SS);
;         for (int r = gw; r < T; r += NGW) {
;             const float* x = p->in[0] + (size_t)r * D; bf16_t* o = (bf16_t*)(ws + WS_XN) + (size_t)r * D; float sq = 0.f;
; #pragma unroll
;             for (int j = 0; j < 8; ++j) { const f32x4 v = ((const f32x4*)x)[lane + 64 * j]; sq += v[0] * v[0] + v[1] * v[1] + v[2] * v[2] + v[3] * v[3];
;                 u32x2 w; w.x = pk2(v[0], v[1]); w.y = pk2(v[2], v[3]); ((u32x2*)o)[lane + 64 * j] = w; }
;             sq = wave_sum(sq);
;             if (lane < 32) ssb[(size_t)r * 32 + lane] = (lane == 0) ? sq : 0.f;
;         }
;     }
.LBB0_82:
	v_add_co_u32_e32 v22, vcc, 0xfffff000, v2
	s_nop 1
	v_addc_co_u32_e32 v23, vcc, -1, v3, vcc
	s_waitcnt lgkmcnt(0)
	global_load_dwordx4 v[14:17], v[22:23], off offset:-3072
	global_load_dwordx4 v[18:21], v[22:23], off offset:-2048
	global_load_dwordx4 v[48:51], v[22:23], off offset:-1024
	global_load_dwordx4 v[28:31], v[2:3], off offset:-4096
	global_load_dwordx4 v[32:35], v[2:3], off offset:-3072
	global_load_dwordx4 v[36:39], v[2:3], off offset:-2048
	global_load_dwordx4 v[40:43], v[2:3], off offset:-1024
	global_load_dwordx4 v[44:47], v[2:3], off
	s_waitcnt vmcnt(7)
	v_cvt_pk_bf16_f32 v52, v14, v15
	v_cvt_pk_bf16_f32 v53, v16, v17
	global_store_dwordx2 v[4:5], v[52:53], off offset:-2048
	v_mul_f32_e32 v13, v15, v15
	v_fmac_f32_e32 v13, v14, v14
	v_fmac_f32_e32 v13, v16, v16
	v_fmac_f32_e32 v13, v17, v17
	s_waitcnt vmcnt(7)
	v_cvt_pk_bf16_f32 v54, v18, v19
	v_cvt_pk_bf16_f32 v55, v20, v21
	global_store_dwordx2 v[4:5], v[54:55], off offset:-1536
	v_mul_f32_e32 v24, v19, v19
	v_fmac_f32_e32 v24, v18, v18
	v_fmac_f32_e32 v24, v20, v20
	v_fmac_f32_e32 v24, v21, v21
	v_add_f32_e32 v13, v13, v24
	s_waitcnt vmcnt(7)
	v_cvt_pk_bf16_f32 v56, v48, v49
	v_cvt_pk_bf16_f32 v57, v50, v51
	global_store_dwordx2 v[4:5], v[56:57], off offset:-1024
	v_mul_f32_e32 v24, v49, v49
	v_fmac_f32_e32 v24, v48, v48
	v_fmac_f32_e32 v24, v50, v50
	v_fmac_f32_e32 v24, v51, v51
	v_add_f32_e32 v13, v13, v24
	s_waitcnt vmcnt(7)
	v_cvt_pk_bf16_f32 v58, v28, v29
	v_cvt_pk_bf16_f32 v59, v30, v31
	global_store_dwordx2 v[4:5], v[58:59], off offset:-512
	v_mul_f32_e32 v24, v29, v29
	v_fmac_f32_e32 v24, v28, v28
	v_fmac_f32_e32 v24, v30, v30
	v_fmac_f32_e32 v24, v31, v31
	v_add_f32_e32 v13, v13, v24
	s_waitcnt vmcnt(7)
	v_cvt_pk_bf16_f32 v60, v32, v33
	v_cvt_pk_bf16_f32 v61, v34, v35
	global_store_dwordx2 v[4:5], v[60:61], off
	v_mul_f32_e32 v24, v33, v33
	v_fmac_f32_e32 v24, v32, v32
	v_fmac_f32_e32 v24, v34, v34
	v_fmac_f32_e32 v24, v35, v35
	v_add_f32_e32 v13, v13, v24
	s_waitcnt vmcnt(7)
	v_cvt_pk_bf16_f32 v62, v36, v37
	v_cvt_pk_bf16_f32 v63, v38, v39
	global_store_dwordx2 v[4:5], v[62:63], off offset:512
	v_mul_f32_e32 v24, v37, v37
	v_fmac_f32_e32 v24, v36, v36
	v_fmac_f32_e32 v24, v38, v38
	v_fmac_f32_e32 v24, v39, v39
	v_add_f32_e32 v13, v13, v24
	s_waitcnt vmcnt(7)
	v_cvt_pk_bf16_f32 v64, v40, v41
	v_cvt_pk_bf16_f32 v65, v42, v43
	global_store_dwordx2 v[4:5], v[64:65], off offset:1024
	v_mul_f32_e32 v24, v41, v41
	v_fmac_f32_e32 v24, v40, v40
	v_fmac_f32_e32 v24, v42, v42
	v_fmac_f32_e32 v24, v43, v43
	v_add_f32_e32 v13, v13, v24
	s_waitcnt vmcnt(7)
	v_cvt_pk_bf16_f32 v66, v44, v45
	v_cvt_pk_bf16_f32 v67, v46, v47
	global_store_dwordx2 v[4:5], v[66:67], off offset:1536
	v_mul_f32_e32 v24, v45, v45
	v_fmac_f32_e32 v24, v44, v44
	v_fmac_f32_e32 v24, v46, v46
	v_fmac_f32_e32 v24, v47, v47
	v_add_f32_e32 v13, v13, v24
	ds_bpermute_b32 v14, v7, v13
	s_waitcnt lgkmcnt(0)
	v_add_f32_e32 v13, v13, v14
	ds_bpermute_b32 v14, v8, v13
	s_waitcnt lgkmcnt(0)
	v_add_f32_e32 v13, v13, v14
	ds_bpermute_b32 v14, v9, v13
	s_waitcnt lgkmcnt(0)
	v_add_f32_e32 v13, v13, v14
	ds_bpermute_b32 v14, v10, v13
	s_waitcnt lgkmcnt(0)
	v_add_f32_e32 v13, v13, v14
	ds_bpermute_b32 v14, v11, v13
	s_waitcnt lgkmcnt(0)
	v_add_f32_e32 v13, v13, v14
	ds_bpermute_b32 v14, v12, v13
	s_and_saveexec_b64 s[22:23], s[4:5]
	s_cbranch_execz .LBB0_81
	s_waitcnt lgkmcnt(0)
	v_add_f32_e32 v13, v13, v14
	v_cndmask_b32_e64 v13, 0, v13, s[6:7]
	global_store_dword v[0:1], v13, off
	s_branch .LBB0_81

; __device__ __forceinline__ PP get_pp() { PP q = (PP)__builtin_amdgcn_kernarg_segment_ptr(); asm volatile("" : "+s"(q)); return q; }
; __device__ __forceinline__ int tid_fresh() { int t = threadIdx.x; asm volatile("" : "+v"(t)); return t; }
; __device__ __forceinline__ int bid_fresh() { int t = blockIdx.x; asm volatile("" : "+s"(t)); return t; }
; __global__ void __launch_bounds__(512, 2) hymba_fwd(Params p_unused) {
;     ...
;     {
;         PP p = get_pp(); const bf16_t* hb = (const bf16_t*)(p->ws + WS_XN); const unsigned char* hl = (const unsigned char*)(p->ws + WS_H); const float* gf = p->in[32]; float* outp = p->out;
;         const int lane = tid_fresh() & 63, gw = bid_fresh() * 8 + (tid_fresh() >> 6), NGW = gridDim.x * 8;
;         for (int r = gw; r < T; r += NGW) {
;             float v[4][8]; float sq = 0.f;
; #pragma unroll
;             for (int j = 0; j < 4; ++j) { float a[8]; unpack8(*(const u32x4*)(hb + (size_t)r * D + (lane + 64 * j) * 8), a);
;                 const u32x2 b = *(const u32x2*)(hl + (size_t)r * D + (lane + 64 * j) * 8);
;                 const hf32x2 l01 = __builtin_amdgcn_cvt_pk_f32_fp8((int)b.x, false), l23 = __builtin_amdgcn_cvt_pk_f32_fp8((int)b.x, true), l45 = __builtin_amdgcn_cvt_pk_f32_fp8((int)b.y, false), l67 = __builtin_amdgcn_cvt_pk_f32_fp8((int)b.y, true);
;                 const float lo[8] = {l01.x, l01.y, l23.x, l23.y, l45.x, l45.y, l67.x, l67.y};
; #pragma unroll
;                 for (int e = 0; e < 8; ++e) { v[j][e] = a[e] + lo[e] * 0.00390625f; sq += v[j][e] * v[j][e]; } }
;             sq = wave_sum(sq);
;             const float rs = 1.0f / sqrtf(sq * (1.0f / D) + EPS);
.LBB0_1496:
	v_mov_b32_e32 v2, v222
	s_lshl_b32 s2, s30, 3
	s_movk_i32 s3, 0x2000
	v_ashrrev_i32_e32 v0, 6, v222
	v_add_u32_e32 v20, s2, v0
	v_cmp_gt_i32_e32 vcc, s3, v20
	s_and_saveexec_b64 s[4:5], vcc
	v_readlane_b32 s12, v255, 5
	v_readlane_b32 s14, v255, 1
	v_readlane_b32 s13, v255, 6
	v_readlane_b32 s15, v255, 2
	s_cbranch_execz .LBB0_1499
	v_lshlrev_b32_e32 v1, 3, v2
	v_and_b32_e32 v18, 0x1f8, v1
	v_and_b32_e32 v1, 64, v226
	v_add_u32_e32 v1, 64, v1
	v_xor_b32_e32 v3, 1, v226
	v_cmp_lt_i32_e32 vcc, v3, v1
	s_load_dwordx4 s[4:7], s[0:1], 0x100
	s_load_dwordx2 s[8:9], s[0:1], 0x110
	v_cndmask_b32_e32 v3, v226, v3, vcc
	v_lshlrev_b32_e32 v21, 2, v3
	v_xor_b32_e32 v3, 2, v226
	v_cmp_lt_i32_e32 vcc, v3, v1
	v_lshlrev_b32_e32 v4, 2, v18
	v_mov_b32_e32 v5, 0
	v_cndmask_b32_e32 v3, v226, v3, vcc
	v_lshlrev_b32_e32 v22, 2, v3
	v_xor_b32_e32 v3, 4, v226
	v_cmp_lt_i32_e32 vcc, v3, v1
	s_ashr_i32 s3, s2, 31
	s_waitcnt lgkmcnt(0)
	v_lshl_add_u64 v[8:9], s[4:5], 0, v[4:5]
	v_cndmask_b32_e32 v3, v226, v3, vcc
	v_lshlrev_b32_e32 v23, 2, v3
	v_xor_b32_e32 v3, 8, v226
	v_cmp_lt_i32_e32 vcc, v3, v1
	v_or_b32_e32 v6, 0x1000, v4
	v_mov_b32_e32 v7, v5
	v_cndmask_b32_e32 v3, v226, v3, vcc
	v_lshlrev_b32_e32 v24, 2, v3
	v_xor_b32_e32 v3, 16, v226
	v_cmp_lt_i32_e32 vcc, v3, v1
	v_or_b32_e32 v4, 0x1800, v4
	v_lshl_add_u64 v[10:11], s[4:5], 0, v[6:7]
	v_cndmask_b32_e32 v3, v226, v3, vcc
	v_lshlrev_b32_e32 v25, 2, v3
	v_xor_b32_e32 v3, 32, v226
	v_cmp_lt_i32_e32 vcc, v3, v1
	v_lshl_add_u64 v[12:13], s[4:5], 0, v[4:5]
	v_and_b32_e32 v6, 63, v2
	v_cndmask_b32_e32 v1, v226, v3, vcc
	v_lshlrev_b32_e32 v26, 2, v1
	v_ashrrev_i32_e32 v1, 31, v0
	v_lshl_add_u64 v[0:1], v[0:1], 0, s[2:3]
	v_lshlrev_b64 v[4:5], 13, v[0:1]
	v_lshl_or_b32 v4, v6, 5, v4
	v_lshl_add_u64 v[2:3], s[6:7], 0, v[4:5]
	s_mov_b64 s[0:1], 0x1810
	v_lshl_add_u64 v[14:15], v[2:3], 0, s[0:1]
	v_lshlrev_b64 v[2:3], 12, v[0:1]
	v_lshl_or_b32 v2, v6, 4, v2
	v_lshlrev_b64 v[0:1], 11, v[0:1]
	v_lshl_add_u64 v[2:3], s[8:9], 0, v[2:3]
	s_mov_b64 s[0:1], 0x1be00800
	v_or_b32_e32 v0, v0, v18
	v_lshl_add_u64 v[16:17], v[2:3], 0, s[0:1]
	v_lshl_add_u64 v[0:1], s[8:9], 0, v[0:1]
	s_mov_b64 s[0:1], 0x17e00400
	s_lshl_b64 s[2:3], s[12:13], 13
	v_lshl_add_u64 v[18:19], v[0:1], 0, s[0:1]
	s_lshl_b64 s[4:5], s[12:13], 11
	s_mov_b64 s[6:7], 0
	s_mov_b32 s8, 0x3b800000
	v_mov_b32_e32 v27, 0x358637bd
	s_mov_b32 s9, 0xf800000
	v_mov_b32_e32 v28, 0x260
	s_movk_i32 s10, 0xf000
	s_movk_i32 s11, 0x1fff
	global_load_dwordx4 v[100:103], v[8:9], off
	global_load_dwordx4 v[104:107], v[8:9], off offset:16
	global_load_dwordx4 v[108:111], v[8:9], off offset:2048
	global_load_dwordx4 v[112:115], v[8:9], off offset:2064
	global_load_dwordx4 v[116:119], v[10:11], off
	global_load_dwordx4 v[120:123], v[10:11], off offset:16
	global_load_dwordx4 v[124:127], v[12:13], off
	global_load_dwordx4 v[128:131], v[12:13], off offset:16
	s_waitcnt vmcnt(0)
.LBB0_1498:
	global_load_dwordx2 v[46:47], v[18:19], off offset:-1024
	global_load_dwordx2 v[48:49], v[18:19], off offset:-512
	global_load_dwordx2 v[50:51], v[18:19], off
	global_load_dwordx2 v[52:53], v[18:19], off offset:512
	global_load_dwordx4 v[30:33], v[16:17], off offset:1024
	global_load_dwordx4 v[34:37], v[16:17], off offset:-2048
	global_load_dwordx4 v[38:41], v[16:17], off offset:-1024
	global_load_dwordx4 v[42:45], v[16:17], off
	v_add_co_u32_e32 v54, vcc, s10, v14
	v_add_u32_e32 v20, s12, v20
	s_nop 0
	v_addc_co_u32_e32 v55, vcc, -1, v15, vcc
	v_lshl_add_u64 v[16:17], v[16:17], 0, s[14:15]
	v_lshl_add_u64 v[18:19], v[18:19], 0, s[4:5]
	s_waitcnt vmcnt(7)
	v_cvt_pk_f32_fp8_e32 v[56:57], v46
	v_cvt_pk_f32_fp8_sdwa v[58:59], v46 src0_sel:WORD_1
	s_waitcnt vmcnt(6)
	v_cvt_pk_f32_fp8_e32 v[66:67], v49
	s_waitcnt vmcnt(4)
	v_cvt_pk_f32_fp8_e32 v[74:75], v52
	v_cvt_pk_f32_fp8_sdwa v[76:77], v52 src0_sel:WORD_1
	v_cvt_pk_f32_fp8_e32 v[78:79], v53
	v_cvt_pk_f32_fp8_sdwa v[52:53], v53 src0_sel:WORD_1
	v_cvt_pk_f32_fp8_e32 v[62:63], v48
	v_cvt_pk_f32_fp8_sdwa v[64:65], v48 src0_sel:WORD_1
	v_cvt_pk_f32_fp8_sdwa v[48:49], v49 src0_sel:WORD_1
	v_cvt_pk_f32_fp8_e32 v[68:69], v50
	v_cvt_pk_f32_fp8_e32 v[60:61], v47
	s_waitcnt vmcnt(3)
	v_lshlrev_b32_e32 v80, 16, v33
	v_and_b32_e32 v81, 0xffff0000, v33
	s_waitcnt vmcnt(2)
	v_lshlrev_b32_e32 v82, 16, v34
	v_and_b32_e32 v83, 0xffff0000, v34
	v_cvt_pk_f32_fp8_sdwa v[70:71], v50 src0_sel:WORD_1
	v_lshlrev_b32_e32 v34, 16, v35
	v_and_b32_e32 v35, 0xffff0000, v35
	s_waitcnt vmcnt(1)
	v_lshlrev_b32_e32 v88, 16, v40
	v_and_b32_e32 v89, 0xffff0000, v40
	v_lshlrev_b32_e32 v96, 16, v32
	v_and_b32_e32 v97, 0xffff0000, v32
	v_pk_fma_f32 v[32:33], v[52:53], s[8:9], v[80:81] op_sel_hi:[1,0,1]
	v_pk_fma_f32 v[52:53], v[56:57], s[8:9], v[82:83] op_sel_hi:[1,0,1]
	v_cvt_pk_f32_fp8_sdwa v[46:47], v47 src0_sel:WORD_1
	v_lshlrev_b32_e32 v40, 16, v41
	v_and_b32_e32 v41, 0xffff0000, v41
	s_waitcnt vmcnt(0)
; __global__ void __launch_bounds__(512, 2) hymba_fwd(Params p_unused) {
;     ...
;             for (int j = 0; j < 4; ++j) { float a[8]; unpack8(*(const u32x4*)(hb + (size_t)r * D + (lane + 64 * j) * 8), a);
;                 const u32x2 b = *(const u32x2*)(hl + (size_t)r * D + (lane + 64 * j) * 8);
;                 const hf32x2 l01 = __builtin_amdgcn_cvt_pk_f32_fp8((int)b.x, false), l23 = __builtin_amdgcn_cvt_pk_f32_fp8((int)b.x, true), l45 = __builtin_amdgcn_cvt_pk_f32_fp8((int)b.y, false), l67 = __builtin_amdgcn_cvt_pk_f32_fp8((int)b.y, true);
;                 const float lo[8] = {l01.x, l01.y, l23.x, l23.y, l45.x, l45.y, l67.x, l67.y};
; #pragma unroll
;                 for (int e = 0; e < 8; ++e) { v[j][e] = a[e] + lo[e] * 0.00390625f; sq += v[j][e] * v[j][e]; } }
;             sq = wave_sum(sq);
	v_lshlrev_b32_e32 v90, 16, v42
	v_and_b32_e32 v91, 0xffff0000, v42
	v_pk_fma_f32 v[34:35], v[58:59], s[8:9], v[34:35] op_sel_hi:[1,0,1]
	v_pk_fma_f32 v[58:59], v[66:67], s[8:9], v[88:89] op_sel_hi:[1,0,1]
	v_pk_mul_f32 v[66:67], v[52:53], v[52:53]
	v_cvt_pk_f32_fp8_e32 v[72:73], v51
	v_lshlrev_b32_e32 v84, 16, v36
	v_and_b32_e32 v85, 0xffff0000, v36
	v_pk_fma_f32 v[40:41], v[48:49], s[8:9], v[40:41] op_sel_hi:[1,0,1]
	v_pk_fma_f32 v[48:49], v[68:69], s[8:9], v[90:91] op_sel_hi:[1,0,1]
	v_pk_mul_f32 v[68:69], v[34:35], v[34:35]
	v_add_f32_e32 v29, v66, v67
	v_lshlrev_b32_e32 v42, 16, v43
	v_and_b32_e32 v43, 0xffff0000, v43
	v_pk_fma_f32 v[56:57], v[60:61], s[8:9], v[84:85] op_sel_hi:[1,0,1]
	v_add_f32_e32 v29, v29, v68
	v_cvt_pk_f32_fp8_sdwa v[50:51], v51 src0_sel:WORD_1
	v_lshlrev_b32_e32 v36, 16, v37
	v_and_b32_e32 v37, 0xffff0000, v37
	v_pk_fma_f32 v[42:43], v[70:71], s[8:9], v[42:43] op_sel_hi:[1,0,1]
	v_pk_mul_f32 v[70:71], v[56:57], v[56:57]
	v_add_f32_e32 v29, v29, v69
	v_lshlrev_b32_e32 v92, 16, v44
	v_and_b32_e32 v93, 0xffff0000, v44
	v_pk_fma_f32 v[36:37], v[46:47], s[8:9], v[36:37] op_sel_hi:[1,0,1]
	v_add_f32_e32 v29, v29, v70
	v_lshlrev_b32_e32 v86, 16, v38
	v_and_b32_e32 v87, 0xffff0000, v38
	v_pk_fma_f32 v[60:61], v[72:73], s[8:9], v[92:93] op_sel_hi:[1,0,1]
	v_pk_mul_f32 v[72:73], v[36:37], v[36:37]
	v_add_f32_e32 v29, v29, v71
	v_lshlrev_b32_e32 v44, 16, v45
	v_and_b32_e32 v45, 0xffff0000, v45
	v_lshlrev_b32_e32 v94, 16, v30
	v_and_b32_e32 v95, 0xffff0000, v30
	v_pk_fma_f32 v[46:47], v[62:63], s[8:9], v[86:87] op_sel_hi:[1,0,1]
	v_add_f32_e32 v29, v29, v72
	v_lshlrev_b32_e32 v38, 16, v39
	v_and_b32_e32 v39, 0xffff0000, v39
	v_pk_fma_f32 v[44:45], v[50:51], s[8:9], v[44:45] op_sel_hi:[1,0,1]
	v_pk_fma_f32 v[50:51], v[74:75], s[8:9], v[94:95] op_sel_hi:[1,0,1]
	v_pk_mul_f32 v[74:75], v[46:47], v[46:47]
	v_add_f32_e32 v29, v29, v73
	v_lshlrev_b32_e32 v30, 16, v31
	v_and_b32_e32 v31, 0xffff0000, v31
	v_pk_fma_f32 v[38:39], v[64:65], s[8:9], v[38:39] op_sel_hi:[1,0,1]
	v_add_f32_e32 v29, v29, v74
	v_pk_fma_f32 v[30:31], v[76:77], s[8:9], v[30:31] op_sel_hi:[1,0,1]
	v_pk_mul_f32 v[76:77], v[38:39], v[38:39]
	v_add_f32_e32 v29, v29, v75
	v_add_f32_e32 v29, v29, v76
	v_pk_fma_f32 v[62:63], v[78:79], s[8:9], v[96:97] op_sel_hi:[1,0,1]
	v_pk_mul_f32 v[78:79], v[58:59], v[58:59]
	v_add_f32_e32 v29, v29, v77
	v_add_f32_e32 v29, v29, v78
	v_pk_mul_f32 v[80:81], v[40:41], v[40:41]
	v_add_f32_e32 v29, v29, v79
	v_add_f32_e32 v29, v29, v80
	v_pk_mul_f32 v[82:83], v[48:49], v[48:49]
	v_add_f32_e32 v29, v29, v81
	v_add_f32_e32 v29, v29, v82
	v_pk_mul_f32 v[84:85], v[42:43], v[42:43]
	v_add_f32_e32 v29, v29, v83
	v_add_f32_e32 v29, v29, v84
	v_pk_mul_f32 v[86:87], v[60:61], v[60:61]
	v_add_f32_e32 v29, v29, v85
	v_add_f32_e32 v29, v29, v86
	v_pk_mul_f32 v[88:89], v[44:45], v[44:45]
	v_add_f32_e32 v29, v29, v87
	v_add_f32_e32 v29, v29, v88
	v_pk_mul_f32 v[90:91], v[50:51], v[50:51]
	v_add_f32_e32 v29, v29, v89
	v_add_f32_e32 v29, v29, v90
	v_pk_mul_f32 v[92:93], v[30:31], v[30:31]
	v_add_f32_e32 v29, v29, v91
	v_add_f32_e32 v29, v29, v92
	v_pk_mul_f32 v[94:95], v[62:63], v[62:63]
	v_add_f32_e32 v29, v29, v93
	v_add_f32_e32 v29, v29, v94
	v_pk_mul_f32 v[64:65], v[32:33], v[32:33]
	v_add_f32_e32 v29, v29, v95
	v_add_f32_e32 v29, v29, v64
	v_add_f32_e32 v29, v29, v65
	ds_bpermute_b32 v64, v21, v29
	s_waitcnt lgkmcnt(0)
	v_add_f32_e32 v29, v29, v64
	ds_bpermute_b32 v64, v22, v29
	s_waitcnt lgkmcnt(0)
	v_add_f32_e32 v29, v29, v64
	ds_bpermute_b32 v64, v23, v29
	s_waitcnt lgkmcnt(0)
; __global__ void __launch_bounds__(512, 2) hymba_fwd(Params p_unused) {
;     ...
;             sq = wave_sum(sq);
;             const float rs = 1.0f / sqrtf(sq * (1.0f / D) + EPS);
; #pragma unroll
;             for (int j = 0; j < 4; ++j) { const f32x4 g0 = *(const f32x4*)(gf + (lane + 64 * j) * 8), g1 = *(const f32x4*)(gf + (lane + 64 * j) * 8 + 4);
;                 float* o = outp + (size_t)r * D + (lane + 64 * j) * 8;
;                 *(f32x4*)o = (f32x4){v[j][0] * rs * g0[0], v[j][1] * rs * g0[1], v[j][2] * rs * g0[2], v[j][3] * rs * g0[3]};
;                 *(f32x4*)(o + 4) = (f32x4){v[j][4] * rs * g1[0], v[j][5] * rs * g1[1], v[j][6] * rs * g1[2], v[j][7] * rs * g1[3]}; }
	v_add_f32_e32 v29, v29, v64
	ds_bpermute_b32 v64, v24, v29
	s_waitcnt lgkmcnt(0)
	v_add_f32_e32 v29, v29, v64
	ds_bpermute_b32 v64, v25, v29
	s_waitcnt lgkmcnt(0)
	v_add_f32_e32 v29, v29, v64
	ds_bpermute_b32 v64, v26, v29
	s_waitcnt lgkmcnt(0)
	v_add_f32_e32 v29, v29, v64
	v_fmamk_f32 v29, v29, 0x3a000000, v27
	v_mul_f32_e32 v64, 0x4f800000, v29
	v_cmp_gt_f32_e32 vcc, s9, v29
	s_nop 1
	v_cndmask_b32_e32 v29, v29, v64, vcc
	v_sqrt_f32_e32 v64, v29
	s_nop 0
	v_add_u32_e32 v65, -1, v64
	v_add_u32_e32 v66, 1, v64
	v_fma_f32 v67, -v65, v64, v29
	v_fma_f32 v68, -v66, v64, v29
	v_cmp_ge_f32_e64 s[0:1], 0, v67
	s_nop 1
	v_cndmask_b32_e64 v64, v64, v65, s[0:1]
	v_cmp_lt_f32_e64 s[0:1], 0, v68
	s_nop 1
	v_cndmask_b32_e64 v64, v64, v66, s[0:1]
	v_mul_f32_e32 v65, 0x37800000, v64
	v_cndmask_b32_e32 v64, v64, v65, vcc
	v_cmp_class_f32_e32 vcc, v29, v28
	s_nop 1
	v_cndmask_b32_e32 v29, v64, v29, vcc
	v_div_scale_f32 v64, s[0:1], v29, v29, 1.0
	v_rcp_f32_e32 v66, v64
	v_div_scale_f32 v65, vcc, 1.0, v29, 1.0
	v_fma_f32 v67, -v64, v66, 1.0
	v_fmac_f32_e32 v66, v67, v66
	v_mul_f32_e32 v67, v65, v66
	v_fma_f32 v68, -v64, v67, v65
	v_fmac_f32_e32 v67, v68, v66
	v_fma_f32 v64, -v64, v67, v65
	v_div_fmas_f32 v64, v64, v66, v67
	v_div_fixup_f32 v64, v64, v29, 1.0
	v_pk_mul_f32 v[52:53], v[64:65], v[52:53] op_sel_hi:[0,1]
	v_pk_mul_f32 v[34:35], v[64:65], v[34:35] op_sel_hi:[0,1]
	v_pk_mul_f32 v[56:57], v[64:65], v[56:57] op_sel_hi:[0,1]
	v_pk_mul_f32 v[36:37], v[64:65], v[36:37] op_sel_hi:[0,1]
	v_pk_mul_f32 v[138:139], v[102:103], v[34:35]
	v_pk_mul_f32 v[136:137], v[100:101], v[52:53]
	v_pk_mul_f32 v[134:135], v[106:107], v[36:37]
	v_pk_mul_f32 v[132:133], v[104:105], v[56:57]
	global_store_dwordx4 v[54:55], v[136:139], off offset:-2064
	global_store_dwordx4 v[54:55], v[132:135], off offset:-2048
	v_pk_mul_f32 v[34:35], v[64:65], v[38:39] op_sel_hi:[0,1]
	v_pk_mul_f32 v[36:37], v[64:65], v[46:47] op_sel_hi:[0,1]
	v_pk_mul_f32 v[38:39], v[64:65], v[40:41] op_sel_hi:[0,1]
	v_pk_mul_f32 v[40:41], v[64:65], v[58:59] op_sel_hi:[0,1]
	v_pk_mul_f32 v[30:31], v[64:65], v[30:31] op_sel_hi:[0,1]
	v_cmp_lt_i32_e32 vcc, s11, v20
	v_pk_mul_f32 v[32:33], v[64:65], v[32:33] op_sel_hi:[0,1]
	s_or_b64 s[6:7], vcc, s[6:7]
	v_pk_mul_f32 v[140:141], v[108:109], v[36:37]
	v_pk_mul_f32 v[142:143], v[110:111], v[34:35]
	v_pk_mul_f32 v[144:145], v[112:113], v[40:41]
	v_pk_mul_f32 v[146:147], v[114:115], v[38:39]
	global_store_dwordx4 v[54:55], v[140:143], off offset:-16
	global_store_dwordx4 v[14:15], v[144:147], off offset:-4096
	v_pk_mul_f32 v[34:35], v[64:65], v[42:43] op_sel_hi:[0,1]
	v_pk_mul_f32 v[36:37], v[64:65], v[48:49] op_sel_hi:[0,1]
	v_pk_mul_f32 v[38:39], v[64:65], v[44:45] op_sel_hi:[0,1]
	v_pk_mul_f32 v[40:41], v[64:65], v[60:61] op_sel_hi:[0,1]
	v_pk_mul_f32 v[148:149], v[116:117], v[36:37]
	v_pk_mul_f32 v[150:151], v[118:119], v[34:35]
	v_pk_mul_f32 v[152:153], v[120:121], v[40:41]
	v_pk_mul_f32 v[154:155], v[122:123], v[38:39]
	global_store_dwordx4 v[14:15], v[148:151], off offset:-2064
	global_store_dwordx4 v[14:15], v[152:155], off offset:-2048
	v_pk_mul_f32 v[34:35], v[64:65], v[50:51] op_sel_hi:[0,1]
	v_pk_mul_f32 v[36:37], v[64:65], v[62:63] op_sel_hi:[0,1]
	v_pk_mul_f32 v[156:157], v[124:125], v[34:35]
	v_pk_mul_f32 v[158:159], v[126:127], v[30:31]
	v_pk_mul_f32 v[160:161], v[128:129], v[36:37]
	v_pk_mul_f32 v[162:163], v[130:131], v[32:33]
	global_store_dwordx4 v[14:15], v[156:159], off offset:-16
	global_store_dwordx4 v[14:15], v[160:163], off
	v_lshl_add_u64 v[14:15], v[14:15], 0, s[2:3]
	s_andn2_b64 exec, exec, s[6:7]
	s_cbranch_execnz .LBB0_1498
